# P0 work index interleaved across XCDs so the workgroups with fewer transpose items are spread over all XCDs
# baseline (speedup 1.0000x reference)
.LBB0_7:
	s_or_b64 exec, exec, s[2:3]
	s_load_dwordx16 s[4:19], s[0:1], 0x0
	v_and_b32_e32 v1, 63, v0
	v_lshrrev_b32_e32 v204, 3, v1
	v_lshlrev_b32_e32 v230, 4, v0
	v_lshlrev_b32_e32 v244, 3, v0
	s_waitcnt lgkmcnt(0)
	v_writelane_b32 v254, s4, 2
	s_nop 1
	v_writelane_b32 v254, s5, 3
	v_writelane_b32 v254, s6, 4
	v_writelane_b32 v254, s7, 5
	v_writelane_b32 v254, s8, 6
	v_writelane_b32 v254, s9, 7
	v_writelane_b32 v254, s10, 8
	v_writelane_b32 v254, s11, 9
	v_writelane_b32 v254, s12, 10
	v_writelane_b32 v254, s13, 11
	v_writelane_b32 v254, s14, 12
	v_writelane_b32 v254, s15, 13
	v_writelane_b32 v254, s16, 14
	v_writelane_b32 v254, s17, 15
	v_writelane_b32 v254, s18, 16
	v_writelane_b32 v254, s19, 17
	s_add_u32 s10, s82, 0x700000
	s_addc_u32 s11, s83, 0
	s_add_u32 s0, s82, 0x100000
	s_addc_u32 s1, s83, 0
	s_add_u32 s60, s82, 0x500000
	s_addc_u32 s61, s83, 0
	s_lshr_b32 s58, s64, 6
	s_lshl_b32 s54, s52, 3
	v_writelane_b32 v254, s0, 18
	s_and_b32 s12, s52, 31
	s_lshl_b32 s12, s12, 3
	s_lshr_b32 s14, s52, 5
	s_add_i32 s12, s12, s14
	s_lshl_b32 s12, s12, 3
	s_add_i32 s12, s12, s58
	s_lshl_b32 s14, s63, 3
	v_writelane_b32 v254, s1, 19
	s_cmpk_gt_i32 s12, 0x16ff
	s_cbranch_scc1 .LBB0_22
	v_mov_b32_e32 v3, 0
	v_and_b32_e32 v6, 56, v244
	s_lshl_b32 s0, s58, 14
	v_lshlrev_b32_e32 v18, 1, v6
	v_mov_b32_e32 v19, v3
	s_add_i32 s0, s0, 0
	v_and_b32_e32 v2, 0x70, v230
	v_lshl_add_u64 v[10:11], s[82:83], 0, v[18:19]
	s_mov_b64 s[2:3], 0x100800
	v_add_u32_e32 v24, s0, v2
	v_mul_u32_u24_e32 v25, 0x84, v204
	v_mul_u32_u24_e32 v8, 0x84, v6
	v_lshlrev_b32_e32 v9, 2, v204
	v_readlane_b32 s16, v254, 2
	v_lshl_add_u64 v[10:11], v[10:11], 0, s[2:3]
	v_readlane_b32 s2, v254, 18
	v_add3_u32 v23, s0, v8, v9
	v_readlane_b32 s17, v254, 3
	v_readlane_b32 s18, v254, 4
	v_readlane_b32 s19, v254, 5
	v_readlane_b32 s20, v254, 6
	v_readlane_b32 s21, v254, 7
	v_readlane_b32 s26, v254, 12
	v_readlane_b32 s27, v254, 13
	v_readlane_b32 s30, v254, 16
	v_readlane_b32 s31, v254, 17
	v_readlane_b32 s3, v254, 19
	s_lshl_b32 s0, s12, 1
	v_add_u32_e32 v24, v24, v25
	s_mov_b32 s1, 0
	v_lshl_add_u64 v[4:5], s[76:77], 0, v[2:3]
	v_or_b32_e32 v20, 8, v204
	v_or_b32_e32 v21, 16, v204
	v_or_b32_e32 v22, 24, v204
	v_lshl_add_u64 v[6:7], s[60:61], 0, v[18:19]
	v_lshl_add_u64 v[8:9], s[30:31], 0, v[2:3]
	v_lshl_add_u64 v[12:13], s[26:27], 0, v[2:3]
	v_lshl_add_u64 v[14:15], s[2:3], 0, v[18:19]
	v_lshl_add_u64 v[16:17], s[20:21], 0, v[2:3]
	v_lshl_add_u64 v[18:19], s[10:11], 0, v[18:19]
	s_lshl_b32 s4, s12, 5
	s_lshl_b32 s5, s14, 5
	s_lshl_b32 s6, s12, 6
	s_lshl_b32 s7, s14, 6
	s_lshl_b32 s8, s12, 2
	s_lshl_b32 s9, s14, 2
	s_add_i32 s13, s0, 0x1d600
	s_lshl_b32 s15, s14, 1
	v_add_u32_e32 v25, 0x420, v24
	v_add_u32_e32 v26, 0x428, v24
	v_add_u32_e32 v27, 0x840, v24
	v_add_u32_e32 v28, 0x848, v24
	v_add_u32_e32 v29, 0xc60, v24
	v_add_u32_e32 v30, 0xc68, v24
	v_add_u32_e32 v31, 0x1080, v24
	v_add_u32_e32 v32, 0x1088, v24
	v_add_u32_e32 v33, 0x14a0, v24
	v_add_u32_e32 v34, 0x14a8, v24
	v_add_u32_e32 v35, 0x18c0, v24
	v_add_u32_e32 v36, 0x18c8, v24
	v_add_u32_e32 v37, 0x1ce0, v24
	v_add_u32_e32 v38, 0x1ce8, v24
	s_movk_i32 s16, 0x7fff
	s_mov_b32 s17, 0xffff0000
	s_mov_b32 s18, 0x8800
	s_mov_b32 s19, s12
	v_readlane_b32 s22, v254, 8
	v_readlane_b32 s23, v254, 9
	v_readlane_b32 s24, v254, 10
	v_readlane_b32 s25, v254, 11
	v_readlane_b32 s28, v254, 14
	v_readlane_b32 s29, v254, 15
	s_branch .LBB0_10
